# placement xiii: like ix but the CU-mates of RWKV chains take no work at all (decode items go to the HGRN mates and to blocks that finish early)
# baseline (speedup 1.0000x reference)
.Lmap_hi_0:
	s_movk_i32 s99, 0x7d0
	s_cmp_lt_u32 s2, 384
	s_cbranch_scc1 .Lmap_done_0
	s_mov_b32 s99, -1
	s_cmp_lt_u32 s2, 448
	s_cbranch_scc1 .Lmap_done_0
	s_sub_u32 s99, s2, 256
